# v23 + gate unit: all loads before the first wait, next queue ticket fetched at unit start
# speedup vs baseline: 1.0101x; 1.0032x over previous
; __global__ void __launch_bounds__(512, 2) mega(Params p) {
;     ...
;             float lam;
;             { const int lane = threadIdx.x & 63; const float a = wave_sum(p.in[12][lane] * p.in[13][lane]), c = wave_sum(p.in[14][lane] * p.in[15][lane]); lam = expf(a) - expf(c) + 0.2f; }
;             unsigned* ctr = (unsigned*)(ws + O_CTR) + 4 * rep5;
;             constexpr int NU_S = 128, NU_P = 1024, NU_G = (256 + 32) * 4;
;             for (;;) {
.LBB0_866:
	s_cmp_lt_i32 s54, 6
	s_cselect_b64 s[0:1], -1, 0
	s_cmp_gt_i32 s55, 5
	s_cselect_b64 s[4:5], -1, 0
	s_and_b64 s[0:1], s[0:1], s[4:5]
	s_andn2_b64 vcc, exec, s[0:1]
	s_cbranch_vccnz .LBB0_1019
	v_readlane_b32 s0, v252, 1
	v_readlane_b32 s1, v252, 2
	s_load_dwordx8 s[8:15], s[0:1], 0x60
	v_and_b32_e32 v0, 63, v208
	v_lshlrev_b32_e32 v0, 2, v0
	s_load_dwordx2 s[4:5], s[0:1], 0x90
	s_load_dwordx4 s[24:27], s[0:1], 0x10
	s_waitcnt lgkmcnt(0)
	global_load_dword v2, v0, s[8:9]
	global_load_dword v3, v0, s[10:11]
	global_load_dword v4, v0, s[12:13]
	global_load_dword v5, v0, s[14:15]
	v_mbcnt_lo_u32_b32 v0, -1, 0
	v_mbcnt_hi_u32_b32 v0, -1, v0
	v_and_b32_e32 v7, 64, v0
	v_xor_b32_e32 v8, 1, v0
	v_add_u32_e32 v7, 64, v7
	v_xor_b32_e32 v9, 2, v0
	v_cmp_lt_i32_e32 vcc, v8, v7
	v_xor_b32_e32 v10, 4, v0
	v_xor_b32_e32 v11, 8, v0
	v_cndmask_b32_e32 v8, v0, v8, vcc
	v_cmp_lt_i32_e32 vcc, v9, v7
	v_xor_b32_e32 v12, 16, v0
	v_xor_b32_e32 v13, 32, v0
	v_cndmask_b32_e32 v9, v0, v9, vcc
	v_cmp_lt_i32_e32 vcc, v10, v7
	v_writelane_b32 v252, s4, 10
	v_mov_b32_e32 v6, 0x7f800000
	v_cndmask_b32_e32 v10, v0, v10, vcc
	v_cmp_lt_i32_e32 vcc, v11, v7
	v_writelane_b32 v252, s5, 11
	s_load_dwordx4 s[16:19], s[0:1], 0x80
	s_load_dwordx4 s[20:23], s[0:1], 0x110
	s_load_dwordx2 s[4:5], s[0:1], 0xa0
	v_cndmask_b32_e32 v11, v0, v11, vcc
	v_cmp_lt_i32_e32 vcc, v12, v7
	s_mov_b32 s0, 0x3fb8aa3b
	s_waitcnt lgkmcnt(0)
	s_add_u32 s60, s22, 0x246a1000
	v_cndmask_b32_e32 v12, v0, v12, vcc
	v_cmp_lt_i32_e32 vcc, v13, v7
	v_lshlrev_b32_e32 v7, 2, v8
	v_lshlrev_b32_e32 v8, 2, v9
	v_lshlrev_b32_e32 v9, 2, v10
	v_lshlrev_b32_e32 v10, 2, v11
	v_cndmask_b32_e32 v0, v0, v13, vcc
	v_lshlrev_b32_e32 v171, 2, v0
	v_lshlrev_b32_e32 v12, 2, v12
	s_addc_u32 s61, s23, 0
	s_add_u32 s62, s22, 0x3001000
	s_addc_u32 s63, s23, 0
	s_add_u32 s64, s22, 0x2f933000
	s_addc_u32 s65, s23, 0
	s_add_u32 s66, s22, 0x267a1000
	s_addc_u32 s67, s23, 0
	s_add_u32 s68, s20, 0x12800000
	v_writelane_b32 v252, s4, 8
	s_addc_u32 s69, s21, 0
	s_add_u32 s70, s22, 0x1e3a1000
	v_writelane_b32 v252, s5, 9
	s_mov_b32 s4, 0xc2ce8ed0
	s_addc_u32 s71, s23, 0
	s_mov_b32 s1, 0x42b17218
	s_add_u32 s72, s22, 0x204a1000
	s_addc_u32 s73, s23, 0
	s_add_u32 s74, s22, 0x225a1000
	s_addc_u32 s75, s23, 0
	s_add_u32 s76, s22, 0x2a9a1000
	s_mov_b32 s38, -2.0
	s_mov_b32 s46, 0xc1000000
	s_mov_b32 s48, 0xc1200000
	s_mov_b32 s50, 0xc1800000
	s_addc_u32 s77, s23, 0
	s_mov_b32 s78, 0xc1900000
	s_mov_b32 s80, 0xc1c00000
	s_mov_b32 s82, 0xc1d00000
	s_mov_b32 s31, 0
	v_mov_b32_e32 v165, 1
	v_mov_b32_e32 v1, 0
	s_mov_b32 s35, 0xf800000
	v_mov_b32_e32 v170, 0x260
	s_movk_i32 s88, 0x140
	s_mov_b32 s89, 0x2a9a1000
	s_movk_i32 s90, 0x90
	s_mov_b32 s39, 0xc0400000
	s_mov_b32 s47, 0xc1100000
	s_mov_b32 s49, 0xc1300000
	s_mov_b32 s51, 0xc1880000
	s_mov_b32 s79, 0xc1980000
	s_mov_b32 s81, 0xc1c80000
	s_mov_b32 s83, 0xc1d80000
	s_waitcnt vmcnt(0)
	v_mul_f32_e32 v11, v2, v3
	ds_bpermute_b32 v11, v7, v11
	v_mul_f32_e32 v13, v4, v5
	ds_bpermute_b32 v7, v7, v13
	v_mov_b32_e32 v172, 0x3727c5ac
	v_mov_b32_e32 v174, 0xf149f2ca
	s_waitcnt lgkmcnt(1)
	v_fmac_f32_e32 v11, v2, v3
	ds_bpermute_b32 v0, v8, v11
	s_waitcnt lgkmcnt(1)
	v_fmac_f32_e32 v7, v4, v5
	ds_bpermute_b32 v2, v8, v7
	s_waitcnt lgkmcnt(1)
	v_add_f32_e32 v0, v11, v0
	ds_bpermute_b32 v3, v9, v0
	s_waitcnt lgkmcnt(1)
	v_add_f32_e32 v2, v7, v2
	ds_bpermute_b32 v4, v9, v2
	s_waitcnt lgkmcnt(1)
	v_add_f32_e32 v0, v0, v3
	ds_bpermute_b32 v3, v10, v0
	s_waitcnt lgkmcnt(1)
	v_add_f32_e32 v2, v2, v4
	ds_bpermute_b32 v4, v10, v2
	s_waitcnt lgkmcnt(1)
	v_add_f32_e32 v0, v0, v3
	ds_bpermute_b32 v3, v12, v0
	s_waitcnt lgkmcnt(1)
	v_add_f32_e32 v2, v2, v4
	ds_bpermute_b32 v4, v12, v2
	s_waitcnt lgkmcnt(1)
	v_add_f32_e32 v0, v0, v3
	ds_bpermute_b32 v3, v171, v0
	s_waitcnt lgkmcnt(1)
	v_add_f32_e32 v2, v2, v4
	ds_bpermute_b32 v4, v171, v2
	s_waitcnt lgkmcnt(1)
	v_add_f32_e32 v0, v0, v3
	v_mul_f32_e32 v3, 0x3fb8aa3b, v0
	s_waitcnt lgkmcnt(0)
	v_add_f32_e32 v2, v2, v4
	v_mul_f32_e32 v4, 0x3fb8aa3b, v2
	v_fma_f32 v5, v0, s0, -v3
	v_rndne_f32_e32 v7, v3
	v_fma_f32 v8, v2, s0, -v4
	v_rndne_f32_e32 v9, v4
	v_fmac_f32_e32 v5, 0x32a5705f, v0
	v_sub_f32_e32 v3, v3, v7
	v_fmac_f32_e32 v8, 0x32a5705f, v2
	v_sub_f32_e32 v4, v4, v9
	v_add_f32_e32 v3, v3, v5
	v_cvt_i32_f32_e32 v7, v7
	v_add_f32_e32 v4, v4, v8
	v_exp_f32_e32 v3, v3
	v_cvt_i32_f32_e32 v9, v9
	v_exp_f32_e32 v4, v4
	v_cmp_ngt_f32_e32 vcc, s4, v0
	v_ldexp_f32 v3, v3, v7
	s_add_i32 s0, 0, 0x23f00
	v_ldexp_f32 v4, v4, v9
	v_cndmask_b32_e32 v3, 0, v3, vcc
	v_cmp_ngt_f32_e32 vcc, s4, v2
	v_mov_b32_e32 v173, s0
	s_nop 0
	v_cndmask_b32_e32 v4, 0, v4, vcc
	v_cmp_nlt_f32_e32 vcc, s1, v0
	s_nop 1
	v_cndmask_b32_e32 v0, v6, v3, vcc
	v_cmp_nlt_f32_e32 vcc, s1, v2
	s_mov_b32 s1, 0x3f4ccccd
	s_nop 0
	v_cndmask_b32_e32 v2, v6, v4, vcc
	v_sub_f32_e32 v0, v0, v2
	v_add_f32_e32 v160, 0x3e4ccccd, v0
	v_mov_b32_e32 v161, v160
	s_mov_b32 s100, 0
	s_branch .LBB0_871

; #define LAS __attribute__((address_space(3)))
; __device__ __forceinline__ int queue_next(unsigned* ctr, LAS unsigned char* lds) {
;     volatile LAS unsigned* w = (volatile LAS unsigned*)(lds + LDS_CTL);
;     if (threadIdx.x == 0) w[0] = atomicAdd(ctr, 1u);
;     __syncthreads();
;     const int u = (int)w[0];
.LBB0_871:
	s_mov_b64 s[6:7], exec
	v_readlane_b32 s4, v252, 6
	v_readlane_b32 s5, v252, 7
	s_and_b64 s[4:5], s[6:7], s[4:5]
	s_mov_b64 exec, s[4:5]
	s_cbranch_execz .LBB0_873
	s_cmpk_eq_u32 s100, 0x5a5a
	s_cbranch_scc0 .Lgp_sync
	s_mov_b32 s100, 0
	s_waitcnt vmcnt(4)
	v_mov_b32_e32 v0, v251
	s_branch .Lgp_pub

; __device__ __forceinline__ int queue_next(unsigned* ctr, LAS unsigned char* lds) {
;     ...
;     if (threadIdx.x == 0) w[0] = atomicAdd(ctr, 1u);
;     __syncthreads();
;     const int u = (int)w[0];
.Lgp_pub:
	v_mov_b32_e32 v2, s0
	ds_write_b32 v2, v0

; #define LAS __attribute__((address_space(3)))
; #define GASP __attribute__((address_space(1)))
; __device__ __forceinline__ void gate_unit(const Params& p, LAS unsigned char* L, int row0, int n, int g, int sample_b) {
;     ...
;     const int tb = wid & 3, dh = wid >> 2;
;     const bool active = tb * 32 < n;
;     const int nks = active ? min((tb + 1) * 2, n / 16) : 0;
;     const int t = tid >> 2, ch = tid & 3; const bool ldr = t < n;
;     f32x4 xv[8], sp[4];
;     if (ldr) { const float* src = GVF + (size_t)(row0 + t) * 512 + g * 128 + ch * 32; const GASP f32x4* sq = (const GASP f32x4*)(GST + (size_t)(row0 + t) * 16);
; #pragma unroll
;         for (int i = 0; i < 8; ++i) xv[i] = *(const GASP f32x4*)(src + 4 * i);
; #pragma unroll
;         for (int i = 0; i < 4; ++i) sp[i] = sq[i]; }
;     bf16x8 wf[8];
;     { const bf16_t* wp = WSB + (size_t)(g * 128 + tb * 32 + r) * 128 + 8 * hi;
; #pragma unroll
;       for (int ks = 0; ks < 8; ++ks) if (ks < nks) wf[ks] = *(const GASP bf16x8*)(wp + ks * 16); }
;     const int te = tb * 32 + r;
;     u32x2 uu[8]; float bias = 0.f;
;     if (active) { const bf16_t* up = UB + (size_t)(row0 + te) * 512 + g * 128 + dh * 64 + 4 * hi; bias = bs[g * 128 + te];
; #pragma unroll
;         for (int i = 0; i < 8; ++i) uu[i] = *(const GASP u32x2*)(up + (i >> 2) * 32 + 8 * (i & 3)); }
; __device__ __forceinline__ int queue_next(unsigned* ctr, LAS unsigned char* lds) {
;     volatile LAS unsigned* w = (volatile LAS unsigned*)(lds + LDS_CTL);
;     if (threadIdx.x == 0) w[0] = atomicAdd(ctr, 1u);
.LBB0_889:
	s_and_b64 vcc, exec, s[6:7]
	s_cbranch_vccz .LBB0_916
	s_mov_b64 s[98:99], exec
	v_cmp_eq_u32_e32 vcc, 0, v208
	s_and_b64 exec, s[98:99], vcc
	s_cbranch_execz .Lgp_skip
	global_atomic_add v251, v1, v165, s[52:53] sc0
.Lgp_skip:
	s_mov_b64 exec, s[98:99]
	s_movk_i32 s100, 0x5a5a
	v_mov_b32_e32 v107, v208
	s_movk_i32 s6, 0x80
	v_ashrrev_i32_e32 v104, 2, v107
	v_cmp_gt_i32_e64 s[12:13], s6, v104
	s_movk_i32 s6, 0x7f
	v_readfirstlane_b32 s15, v107
	v_cmp_lt_i32_e32 vcc, s6, v104
	s_and_saveexec_b64 s[6:7], vcc
	s_xor_b64 s[6:7], exec, s[6:7]
	s_lshl_b32 s8, s5, 7
	s_or_saveexec_b64 s[6:7], s[6:7]
	v_and_b32_e32 v105, 3, v107
	s_lshl_b32 s14, s14, 7
	v_mov_b32_e32 v0, s8
	v_lshlrev_b32_e32 v102, 7, v105
	s_xor_b64 exec, exec, s[6:7]
	s_cbranch_execz .LBB0_894
	s_waitcnt vmcnt(7)
	v_add_u32_e32 v2, s14, v104
	v_ashrrev_i32_e32 v3, 31, v2
	v_lshlrev_b64 v[4:5], 11, v[2:3]
	v_lshl_add_u64 v[4:5], s[66:67], 0, v[4:5]
	s_lshl_b32 s30, s5, 9
	v_lshl_add_u64 v[4:5], v[4:5], 0, s[30:31]
	v_mov_b32_e32 v103, v1
	s_waitcnt vmcnt(0)
	v_lshl_add_u64 v[14:15], v[4:5], 0, v[102:103]
	v_lshlrev_b64 v[2:3], 6, v[2:3]
	v_lshl_add_u64 v[16:17], s[64:65], 0, v[2:3]
	global_load_dwordx4 v[18:21], v[14:15], off offset:48
	global_load_dwordx4 v[22:25], v[14:15], off offset:32
	global_load_dwordx4 v[30:33], v[14:15], off offset:16
	global_load_dwordx4 v[62:65], v[14:15], off
	global_load_dwordx4 v[2:5], v[14:15], off offset:112
	global_load_dwordx4 v[6:9], v[14:15], off offset:96
	global_load_dwordx4 v[10:13], v[14:15], off offset:80
	global_load_dwordx4 v[26:29], v[14:15], off offset:64
	global_load_dwordx4 v[66:69], v[16:17], off offset:48
	global_load_dwordx4 v[70:73], v[16:17], off offset:32
	global_load_dwordx4 v[74:77], v[16:17], off offset:16
	global_load_dwordx4 v[78:81], v[16:17], off
	v_readlane_b32 s98, v252, 10
	v_readlane_b32 s99, v252, 11
	v_lshl_add_u32 v250, v0, 2, v102
	global_load_dwordx4 v[128:131], v250, s[18:19]
	global_load_dwordx4 v[132:135], v250, s[18:19] offset:16
	global_load_dwordx4 v[136:139], v250, s[18:19] offset:32
	global_load_dwordx4 v[140:143], v250, s[18:19] offset:48
	global_load_dwordx4 v[144:147], v250, s[18:19] offset:64
	global_load_dwordx4 v[148:151], v250, s[18:19] offset:80
	global_load_dwordx4 v[152:155], v250, s[18:19] offset:96
	global_load_dwordx4 v[156:159], v250, s[18:19] offset:112
	global_load_dwordx4 v[176:179], v250, s[98:99]
	global_load_dwordx4 v[180:183], v250, s[98:99] offset:16
	global_load_dwordx4 v[184:187], v250, s[98:99] offset:32
	global_load_dwordx4 v[188:191], v250, s[98:99] offset:48
	global_load_dwordx4 v[192:195], v250, s[98:99] offset:64
	global_load_dwordx4 v[196:199], v250, s[98:99] offset:80
	global_load_dwordx4 v[200:203], v250, s[98:99] offset:96
	global_load_dwordx4 v[204:207], v250, s[98:99] offset:112
	s_lshl_b32 s5, s5, 7
	v_mov_b32_e32 v0, s5
.LBB0_894:
	s_or_b64 exec, exec, s[6:7]
	s_bfe_u32 s5, s15, 0x20006
	v_and_b32_e32 v82, 31, v107
	s_lshl_b32 s28, s5, 5
	v_or3_b32 v14, s28, v0, v82
	v_bfe_u32 v83, v107, 5, 1
	v_lshlrev_b32_e32 v14, 8, v14
	v_mov_b32_e32 v15, v1
	v_lshl_add_u64 v[14:15], s[62:63], 0, v[14:15]
	v_lshlrev_b32_e32 v16, 4, v83
	v_mov_b32_e32 v17, v1
	v_lshl_add_u64 v[36:37], v[14:15], 0, v[16:17]
	global_load_dwordx4 v[14:17], v[36:37], off
	global_load_dwordx4 v[58:61], v[36:37], off offset:32
	s_cmp_lg_u32 s5, 0
	s_cselect_b64 s[6:7], -1, 0
	s_cmp_eq_u32 s5, 0
	s_cbranch_scc1 .LBB0_896
	global_load_dwordx4 v[54:57], v[36:37], off offset:64

; #define LAS __attribute__((address_space(3)))
; #define GASP __attribute__((address_space(1)))
; __device__ __forceinline__ void gate_unit(const Params& p, LAS unsigned char* L, int row0, int n, int g, int sample_b) {
;     ...
;     if (active) { const bf16_t* up = UB + (size_t)(row0 + te) * 512 + g * 128 + dh * 64 + 4 * hi; bias = bs[g * 128 + te];
; #pragma unroll
;         for (int i = 0; i < 8; ++i) uu[i] = *(const GASP u32x2*)(up + (i >> 2) * 32 + 8 * (i & 3)); }
;     if (ldr) {
;         float s = 0.f, q = 0.f;
; #pragma unroll
;         for (int i = 0; i < 4; ++i) { s += sp[i][0] + sp[i][2]; q += sp[i][1] + sp[i][3]; }
;         const float mean = s * (1.f / 512.f), rstd = 1.f / sqrtf(q * (1.f / 512.f) - mean * mean + LN_EPS);
;         const float* gp = lng + g * 128 + ch * 32; const float* bp = lnb + g * 128 + ch * 32;
; #pragma unroll
;         for (int i = 0; i < 4; ++i) {
;             const f32x4 ya = (xv[2 * i] - mean) * rstd * *(const GASP f32x4*)(gp + 8 * i) + *(const GASP f32x4*)(bp + 8 * i);
;             const f32x4 yc = (xv[2 * i + 1] - mean) * rstd * *(const GASP f32x4*)(gp + 8 * i + 4) + *(const GASP f32x4*)(bp + 8 * i + 4);
;             u32x4 w; w.x = pk2(ya[0], ya[1]); w.y = pk2(ya[2], ya[3]); w.z = pk2(yc[0], yc[1]); w.w = pk2(yc[2], yc[3]);
;             *(LAS u32x4*)(L + t * DA_VRS + ch * 64 + i * 16) = w;
.LBB0_906:
	v_or_b32_e32 v82, s28, v82
	v_or_b32_e32 v106, s14, v82
	s_ashr_i32 s5, s15, 8
	v_lshlrev_b32_e32 v84, 10, v106
	v_mov_b32_e32 v85, v1
	v_lshl_add_u64 v[84:85], s[60:61], 0, v[84:85]
	s_lshl_b32 s84, s5, 6
	v_lshl_add_u64 v[84:85], v[0:1], 1, v[84:85]
	s_ashr_i32 s85, s84, 31
	v_readlane_b32 s14, v252, 8
	v_lshlrev_b32_e32 v100, 3, v83
	v_lshl_add_u64 v[84:85], s[84:85], 1, v[84:85]
	v_mov_b32_e32 v101, v1
	v_or_b32_e32 v86, v0, v82
	v_mov_b32_e32 v87, v1
	v_readlane_b32 s15, v252, 9
	v_lshl_add_u64 v[84:85], v[84:85], 0, v[100:101]
	s_nop 0
	v_lshl_add_u64 v[86:87], v[86:87], 2, s[14:15]
	global_load_dword v82, v[86:87], off
	global_load_dwordx2 v[98:99], v[84:85], off
	global_load_dwordx2 v[96:97], v[84:85], off offset:16
	global_load_dwordx2 v[94:95], v[84:85], off offset:32
	global_load_dwordx2 v[92:93], v[84:85], off offset:48
	global_load_dwordx2 v[90:91], v[84:85], off offset:64
	global_load_dwordx2 v[88:89], v[84:85], off offset:80
	global_load_dwordx2 v[86:87], v[84:85], off offset:96
	s_nop 0
	global_load_dwordx2 v[84:85], v[84:85], off offset:112
	s_waitcnt vmcnt(0)
	s_and_saveexec_b64 s[86:87], s[12:13]
	s_cbranch_execz .LBB0_908
	v_pk_add_f32 v[78:79], v[78:79], v[80:81]
	v_pk_add_f32 v[74:75], v[74:75], v[76:77]
	v_pk_add_f32 v[78:79], v[78:79], 0 op_sel_hi:[1,0]
	v_pk_add_f32 v[70:71], v[70:71], v[72:73]
	v_pk_add_f32 v[74:75], v[74:75], v[78:79]
	v_pk_add_f32 v[66:67], v[66:67], v[68:69]
	v_pk_add_f32 v[70:71], v[70:71], v[74:75]
	s_mov_b32 s12, 0x3b000000
	v_pk_add_f32 v[66:67], v[66:67], v[70:71]
	v_mov_b32_e32 v103, v1
	v_pk_mul_f32 v[78:79], v[66:67], s[12:13] op_sel_hi:[1,0]
	s_nop 0
	v_fma_f32 v66, -v78, v78, v79
	v_add_f32_e32 v66, 0x3727c5ac, v66
	v_cmp_gt_f32_e32 vcc, s35, v66
	v_mul_f32_e32 v67, 0x4f800000, v66
	v_sub_f32_e32 v65, v65, v78
	v_cndmask_b32_e32 v66, v66, v67, vcc
	v_sqrt_f32_e32 v67, v66
	v_sub_f32_e32 v64, v64, v78
	v_sub_f32_e32 v63, v63, v78
	v_sub_f32_e32 v62, v62, v78
	v_add_u32_e32 v68, -1, v67
	v_fma_f32 v69, -v68, v67, v66
	v_cmp_ge_f32_e64 s[12:13], 0, v69
	v_add_u32_e32 v69, 1, v67
	v_sub_f32_e32 v33, v33, v78
	v_cndmask_b32_e64 v68, v67, v68, s[12:13]
	v_fma_f32 v67, -v69, v67, v66
	v_cmp_lt_f32_e64 s[12:13], 0, v67
	v_sub_f32_e32 v32, v32, v78
	v_sub_f32_e32 v31, v31, v78
	v_cndmask_b32_e64 v67, v68, v69, s[12:13]
	v_mul_f32_e32 v68, 0x37800000, v67
	v_cndmask_b32_e32 v67, v67, v68, vcc
	v_cmp_class_f32_e32 vcc, v66, v170
	v_sub_f32_e32 v30, v30, v78
	v_sub_f32_e32 v25, v25, v78
	v_cndmask_b32_e32 v66, v67, v66, vcc
	v_div_scale_f32 v67, s[12:13], v66, v66, 1.0
	v_rcp_f32_e32 v68, v67
	v_readlane_b32 s12, v252, 10
	v_readlane_b32 s13, v252, 11
	v_sub_f32_e32 v24, v24, v78
	v_fma_f32 v69, -v67, v68, 1.0
	v_fmac_f32_e32 v68, v69, v68
	v_div_scale_f32 v69, vcc, 1.0, v66, 1.0
	v_mul_f32_e32 v70, v69, v68
	v_fma_f32 v71, -v67, v70, v69
	v_fmac_f32_e32 v70, v71, v68
	v_fma_f32 v67, -v67, v70, v69
	v_div_fmas_f32 v67, v67, v68, v70
	v_lshlrev_b64 v[68:69], 2, v[0:1]
	v_div_fixup_f32 v80, v67, v66, 1.0
	v_lshl_add_u64 v[66:67], s[18:19], 0, v[68:69]
	v_lshl_add_u64 v[68:69], s[12:13], 0, v[68:69]
	v_lshl_add_u64 v[66:67], v[66:67], 0, v[102:103]
	v_lshl_add_u64 v[74:75], v[68:69], 0, v[102:103]
	v_mul_lo_u32 v68, v104, s88
	v_lshlrev_b32_e32 v69, 6, v105
	v_add3_u32 v79, 0, v68, v69
	v_pk_mul_f32 v[72:73], v[62:63], v[80:81] op_sel_hi:[1,0]
	v_pk_mul_f32 v[76:77], v[64:65], v[80:81] op_sel_hi:[1,0]
	v_pk_mul_f32 v[30:31], v[30:31], v[80:81] op_sel_hi:[1,0]
	v_pk_mul_f32 v[32:33], v[32:33], v[80:81] op_sel_hi:[1,0]
	v_sub_f32_e32 v23, v23, v78
	v_sub_f32_e32 v22, v22, v78
	v_sub_f32_e32 v21, v21, v78
	v_sub_f32_e32 v20, v20, v78
	v_sub_f32_e32 v19, v19, v78
	v_sub_f32_e32 v18, v18, v78
	v_pk_mul_f32 v[22:23], v[22:23], v[80:81] op_sel_hi:[1,0]
	v_pk_mul_f32 v[24:25], v[24:25], v[80:81] op_sel_hi:[1,0]
	v_pk_mul_f32 v[18:19], v[18:19], v[80:81] op_sel_hi:[1,0]
	v_pk_mul_f32 v[20:21], v[20:21], v[80:81] op_sel_hi:[1,0]
	v_sub_f32_e32 v13, v13, v78
	v_sub_f32_e32 v12, v12, v78
	v_sub_f32_e32 v11, v11, v78
	v_sub_f32_e32 v10, v10, v78
	v_pk_mul_f32 v[10:11], v[10:11], v[80:81] op_sel_hi:[1,0]
	v_pk_mul_f32 v[12:13], v[12:13], v[80:81] op_sel_hi:[1,0]
	v_sub_f32_e32 v9, v9, v78
	v_sub_f32_e32 v8, v8, v78
	v_sub_f32_e32 v7, v7, v78
	v_sub_f32_e32 v6, v6, v78
	v_sub_f32_e32 v5, v5, v78
	v_sub_f32_e32 v4, v4, v78
	v_sub_f32_e32 v3, v3, v78
	v_sub_f32_e32 v2, v2, v78
	v_pk_mul_f32 v[6:7], v[6:7], v[80:81] op_sel_hi:[1,0]
	v_pk_mul_f32 v[8:9], v[8:9], v[80:81] op_sel_hi:[1,0]
	v_pk_mul_f32 v[2:3], v[2:3], v[80:81] op_sel_hi:[1,0]
	v_pk_mul_f32 v[4:5], v[4:5], v[80:81] op_sel_hi:[1,0]
	v_pk_fma_f32 v[24:25], v[24:25], v[138:139], v[186:187]
	v_pk_fma_f32 v[104:105], v[32:33], v[134:135], v[182:183]
	v_pk_fma_f32 v[76:77], v[76:77], v[130:131], v[178:179]
	v_pk_fma_f32 v[72:73], v[72:73], v[128:129], v[176:177]
	v_pk_fma_f32 v[32:33], v[30:31], v[132:133], v[180:181]
	v_cvt_pk_bf16_f32 v30, v72, v73
	v_cvt_pk_bf16_f32 v31, v76, v77
	v_cvt_pk_bf16_f32 v32, v32, v33
	v_cvt_pk_bf16_f32 v33, v104, v105
	ds_write_b128 v79, v[30:33]
	v_pk_fma_f32 v[22:23], v[22:23], v[136:137], v[184:185]
	v_pk_fma_f32 v[30:31], v[20:21], v[142:143], v[190:191]
	v_pk_fma_f32 v[20:21], v[18:19], v[140:141], v[188:189]
	v_cvt_pk_bf16_f32 v18, v22, v23
	v_cvt_pk_bf16_f32 v19, v24, v25
	v_cvt_pk_bf16_f32 v20, v20, v21
	v_cvt_pk_bf16_f32 v21, v30, v31
	ds_write_b128 v79, v[18:21] offset:16
	v_sub_f32_e32 v19, v29, v78
	v_sub_f32_e32 v18, v28, v78
	v_sub_f32_e32 v21, v27, v78
	v_sub_f32_e32 v20, v26, v78
	v_pk_mul_f32 v[102:103], v[20:21], v[80:81] op_sel_hi:[1,0]
	v_pk_mul_f32 v[104:105], v[18:19], v[80:81] op_sel_hi:[1,0]
	s_nop 0
	s_nop 0
	v_pk_fma_f32 v[8:9], v[8:9], v[154:155], v[202:203]
	v_pk_fma_f32 v[64:65], v[12:13], v[150:151], v[198:199]
	v_pk_fma_f32 v[72:73], v[104:105], v[146:147], v[194:195]
	v_pk_fma_f32 v[70:71], v[102:103], v[144:145], v[192:193]
	v_pk_fma_f32 v[12:13], v[10:11], v[148:149], v[196:197]
	v_cvt_pk_bf16_f32 v10, v70, v71
	v_cvt_pk_bf16_f32 v11, v72, v73
	v_cvt_pk_bf16_f32 v12, v12, v13
	v_cvt_pk_bf16_f32 v13, v64, v65
	ds_write_b128 v79, v[10:13] offset:32
	v_pk_fma_f32 v[6:7], v[6:7], v[152:153], v[200:201]
	v_pk_fma_f32 v[10:11], v[4:5], v[158:159], v[206:207]
	v_pk_fma_f32 v[4:5], v[2:3], v[156:157], v[204:205]
	v_cvt_pk_bf16_f32 v2, v6, v7
	v_cvt_pk_bf16_f32 v3, v8, v9
	v_cvt_pk_bf16_f32 v4, v4, v5
	v_cvt_pk_bf16_f32 v5, v10, v11
	ds_write_b128 v79, v[2:5] offset:48
